# mixer-C rope-key tile also staged row-contiguous: 16 rows x 64 B per LDS-DMA instruction with swizzled LDS image
# baseline (speedup 1.0000x reference)
.LBB0_563:
	s_andn2_b64 vcc, exec, s[4:5]
	s_cbranch_vccnz .LBB0_569
	s_lshl_b32 s88, s39, 3
	s_cmp_lt_i32 s50, 0
	s_mov_b64 s[4:5], -1
	s_cbranch_scc1 .LBB0_566
	v_mov_b32_e32 v247, s50
	v_lshrrev_b32_e32 v246, 2, v214
	v_lshl_add_u32 v246, v247, 4, v246
	v_and_b32_e32 v248, 3, v214
	v_bfe_u32 v247, v214, 4, 2
	v_xor_b32_e32 v248, v248, v247
	v_lshlrev_b32_e32 v248, 4, v248
	v_add_u32_e32 v248, 0x80, v248
	v_mov_b32_e32 v249, 0
	v_mov_b64_e32 v[2:3], s[22:23]
	v_mad_u64_u32 v[2:3], s[4:5], v246, s73, v[2:3]
	v_lshl_add_u64 v[2:3], v[2:3], 0, v[248:249]
	v_lshl_add_u64 v[2:3], v[2:3], 0, s[92:93]
	s_mov_b64 s[4:5], 0

; #define GL(T, p) (*(const __attribute__((address_space(1))) T*)(p))
; template <int DQK, int MODE> __device__ __forceinline__ void unit(const Desc& d, int q0, ATT_LAS char* shm, const float* biasg, float sinkl2) {
;     ...
;     if (MODE == 1) { const int idx = tid - 128; bias_l[tid] = (idx >= 0 && idx <= 256) ? biasg[idx] : NEGBIG; }
;     ATT_DMA(t0, 0);
;     bf16x8 qr[ND0];
;     { const bf16* Qw = d.Q + (size_t)(qw + r32) * d.ldq + hi * 8;
; #pragma unroll
;       for (int d0 = 0; d0 < ND0; ++d0) qr[d0] = GL(bf16x8, Qw + d0 * 16); }
;     float mhat = 0.f, l_reg = 0.f; f32x16 o[2]; o[0] = f32x16{}; o[1] = f32x16{}; f32x16 negm = f32x16{};
;     constexpr bool MSUM = true;
;     f32x16 lacc = f32x16{}; const bf16x8 ones8 = (bf16x8){0x3f80, 0x3f80, 0x3f80, 0x3f80, 0x3f80, 0x3f80, 0x3f80, 0x3f80};
;     const int vb0 = (int)(lds0 + LDS_V) + ((lane >> 4) & 1) * 32 + (lane & 3) * 8 + (4 * hi + ((lane & 15) >> 2)) * 64;
;     int buf = 0;
.LBB0_569:
	s_add_i32 s4, s49, s80
	s_lshl_b32 s4, s4, 8
	s_lshl_b32 s5, s50, 5
	s_add_i32 s28, s5, s4
	s_lshl_b32 s4, s50, 4
	v_lshrrev_b32_e32 v0, 2, v214
	v_and_or_b32 v0, s4, 48, v0
	s_ashr_i32 s4, s36, 3
	s_andn2_b32 s4, s4, 31
	v_lshlrev_b32_e32 v0, 10, v0
	s_ashr_i32 s5, s4, 31
	v_lshlrev_b32_e32 v215, 3, v4
	v_lshl_add_u64 v[2:3], s[26:27], 0, v[0:1]
	s_lshl_b64 s[42:43], s[4:5], 1
	v_and_b32_e32 v5, 24, v215
	v_lshl_add_u64 v[2:3], v[2:3], 0, s[42:43]
	v_lshlrev_b32_e32 v6, 1, v5
	v_mov_b32_e32 v7, v1
	v_lshl_add_u64 v[2:3], v[2:3], 0, v[6:7]
	v_and_b32_e32 v216, 31, v4
	v_lshl_add_u64 v[2:3], v[2:3], 0, s[90:91]
	s_lshl_b32 s29, s50, 10
	v_lshrrev_b32_e32 v217, 5, v214
	s_add_i32 s51, s29, s62
	s_mov_b32 s4, m0
	s_mov_b32 m0, s51
	s_nop 0
	global_load_lds_dwordx4 v[2:3], off
	s_mov_b32 m0, s4
	v_or_b32_e32 v6, s28, v216
	v_mov_b64_e32 v[2:3], s[6:7]
	v_mad_i64_i32 v[2:3], s[4:5], v6, s81, v[2:3]
	v_lshlrev_b32_e32 v208, 4, v217
	v_mov_b32_e32 v209, v1
	v_lshl_add_u64 v[2:3], v[2:3], 0, v[208:209]
	global_load_dwordx4 v[178:181], v[2:3], off
	global_load_dwordx4 v[182:185], v[2:3], off offset:32
	global_load_dwordx4 v[186:189], v[2:3], off offset:64
	global_load_dwordx4 v[190:193], v[2:3], off offset:96
	global_load_dwordx4 v[194:197], v[2:3], off offset:128
	global_load_dwordx4 v[198:201], v[2:3], off offset:160
	s_and_b32 s37, s36, 0x3fffffc0
	s_lshl_b32 s4, s37, 2
	s_add_i32 s54, s4, 0
	s_cmp_gt_i32 s50, 7
	s_cselect_b64 s[36:37], -1, 0
	s_lshl_b32 s60, s50, 3
	s_ashr_i32 s69, s60, 31
	s_mov_b32 s61, s89
	s_cmp_gt_i32 s50, -1
	s_mov_b32 s68, s60
	s_cselect_b64 s[58:59], -1, 0
	s_lshl_b32 s55, s39, 10
	s_lshl_b64 s[60:61], s[60:61], 1
	s_add_u32 s64, s22, s60
	v_lshlrev_b32_e32 v6, 4, v4
	s_addc_u32 s65, s23, s61
	s_lshl_b64 s[60:61], s[88:89], 1
	v_lshlrev_b32_e32 v2, 1, v4
	v_lshlrev_b32_e32 v3, 8, v217
	v_and_b32_e32 v6, 0xc0, v6
	s_add_u32 s74, s22, s60
	v_and_b32_e32 v2, 32, v2
	s_addc_u32 s75, s23, s61
	v_or3_b32 v3, v6, v3, v5
	v_add3_u32 v219, v2, s62, v3
	v_and_b32_e32 v2, 3, v4
	s_add_u32 s42, s11, s42
	v_lshl_or_b32 v0, v2, 4, v0
	s_addc_u32 s43, s46, s43
	v_lshl_add_u64 v[210:211], s[42:43], 0, v[0:1]
	s_lshl_b64 s[42:43], s[68:69], 1
	v_lshlrev_b32_e32 v7, 10, v217
	v_lshlrev_b32_e32 v8, 4, v216
	s_mov_b32 s42, s47
	v_lshrrev_b32_e32 v246, 4, v216
	v_and_b32_e32 v247, 15, v216
	v_bfe_u32 v248, v216, 2, 2
	v_lshlrev_b32_e32 v246, 10, v246
	v_lshl_add_u32 v246, v247, 6, v246
	v_add_u32_e32 v246, 0x2000, v246
	v_xor_b32_e32 v247, v217, v248
	v_lshl_add_u32 v209, v247, 4, v246
	v_add_u32_e32 v247, 2, v217
	v_xor_b32_e32 v247, v247, v248
	v_lshl_add_u32 v208, v247, 4, v246
	v_lshrrev_b32_e32 v242, 3, v216
	v_and_b32_e32 v243, 7, v216
	v_bfe_u32 v244, v216, 1, 2
	v_bfe_u32 v245, v216, 4, 1
	v_lshl_or_b32 v244, v245, 2, v244
	v_lshlrev_b32_e32 v242, 10, v242
	v_lshl_add_u32 v242, v243, 7, v242
	v_add_u32_e32 v245, 0, v217
	v_xor_b32_e32 v245, v245, v244
	v_lshl_add_u32 v221, v245, 4, v242
	v_add_u32_e32 v245, 2, v217
	v_xor_b32_e32 v245, v245, v244
	v_lshl_add_u32 v223, v245, 4, v242
	v_add_u32_e32 v245, 4, v217
	v_xor_b32_e32 v245, v245, v244
	v_lshl_add_u32 v252, v245, 4, v242
	v_add_u32_e32 v245, 6, v217
	v_xor_b32_e32 v245, v245, v244
	v_lshl_add_u32 v253, v245, 4, v242
	v_lshlrev_b32_e32 v0, 10, v238
	s_mov_b32 s43, s48
	v_mov_b32_e32 v2, v1
	v_mov_b32_e32 v3, v1
	v_mov_b32_e32 v4, v1
	v_mov_b32_e32 v5, v1
	v_mov_b32_e32 v6, v1
	v_mov_b32_e32 v7, v1
	v_mov_b32_e32 v8, v1
	v_mov_b32_e32 v9, v1
	v_mov_b32_e32 v10, v1
	v_mov_b32_e32 v11, v1
	v_mov_b32_e32 v12, v1
	v_mov_b32_e32 v13, v1
	v_mov_b32_e32 v14, v1
	v_mov_b32_e32 v15, v1
	v_mov_b32_e32 v16, v1
	v_mov_b32_e32 v17, v1
	v_mov_b32_e32 v18, v1
	v_mov_b32_e32 v19, v1
	v_mov_b32_e32 v20, v1
	v_mov_b32_e32 v21, v1
	v_mov_b32_e32 v22, v1
	v_mov_b32_e32 v23, v1
	v_mov_b32_e32 v24, v1
	v_mov_b32_e32 v25, v1
	v_mov_b32_e32 v26, v1
	v_mov_b32_e32 v27, v1
	v_mov_b32_e32 v28, v1
	v_mov_b32_e32 v29, v1
	v_mov_b32_e32 v30, v1
	v_mov_b32_e32 v31, v1
	v_lshl_add_u64 v[212:213], s[42:43], 0, v[0:1]
	v_lshl_add_u64 v[212:213], v[212:213], 0, v[236:237]
	v_mov_b32_e32 v0, v1
	v_mov_b32_e32 v220, 0
	v_mov_b64_e32 v[32:33], v[30:31]
	v_cmp_gt_u32_e64 s[4:5], 32, v214
	v_lshl_add_u32 v218, v216, 2, s54
	s_mov_b32 s60, 0
	v_mov_b32_e32 v82, v1
	v_mov_b32_e32 v83, v1
	v_mov_b32_e32 v84, v1
	v_mov_b32_e32 v85, v1
	v_mov_b32_e32 v86, v1
	v_mov_b32_e32 v87, v1
	v_mov_b32_e32 v88, v1
	v_mov_b32_e32 v89, v1
	v_mov_b32_e32 v90, v1
	v_mov_b32_e32 v91, v1
	v_mov_b32_e32 v92, v1
	v_mov_b32_e32 v93, v1
	v_mov_b32_e32 v94, v1
	v_mov_b32_e32 v95, v1
	v_mov_b32_e32 v96, v1
	v_mov_b32_e32 v97, v1
	s_mov_b64 s[96:97], 0
	s_mov_b32 s61, 0
	v_mov_b64_e32 v[30:31], v[28:29]
	v_mov_b64_e32 v[28:29], v[26:27]
	v_mov_b64_e32 v[26:27], v[24:25]
	v_mov_b64_e32 v[24:25], v[22:23]
	v_mov_b64_e32 v[22:23], v[20:21]
	v_mov_b64_e32 v[20:21], v[18:19]
	v_mov_b64_e32 v[18:19], v[16:17]
	v_mov_b64_e32 v[16:17], v[14:15]
	v_mov_b64_e32 v[14:15], v[12:13]
	v_mov_b64_e32 v[12:13], v[10:11]
	v_mov_b64_e32 v[10:11], v[8:9]
	v_mov_b64_e32 v[8:9], v[6:7]
	v_mov_b64_e32 v[6:7], v[4:5]
	v_mov_b64_e32 v[4:5], v[2:3]
	v_mov_b64_e32 v[2:3], v[0:1]
	v_mov_b32_e32 v66, 0
	v_mov_b32_e32 v67, v220
	v_mov_b32_e32 v68, v220
	v_mov_b32_e32 v69, v220
	v_mov_b32_e32 v70, v220
	v_mov_b32_e32 v71, v220
	v_mov_b32_e32 v72, v220
	v_mov_b32_e32 v73, v220
	v_mov_b32_e32 v74, v220
	v_mov_b32_e32 v75, v220
	v_mov_b32_e32 v76, v220
	v_mov_b32_e32 v77, v220
	v_mov_b32_e32 v78, v220
	v_mov_b32_e32 v79, v220
	v_mov_b32_e32 v80, v220
	v_mov_b32_e32 v81, v220
	s_branch .LBB0_572

; template <int DQK, int MODE> __device__ __forceinline__ void unit(const Desc& d, int q0, ATT_LAS char* shm, const float* biasg, float sinkl2) {
;     ...
;         if (t + 1 < t1) ATT_DMA(t + 1, buf ^ 1);
.LBB0_579:
	s_andn2_b64 vcc, exec, s[34:35]
	s_cbranch_vccnz .LBB0_585
	s_andn2_b64 vcc, exec, s[58:59]
	s_mov_b64 s[42:43], -1
	s_cbranch_vccnz .LBB0_582
	v_mov_b32_e32 v247, s50
	v_lshrrev_b32_e32 v246, 2, v214
	v_lshl_add_u32 v246, v247, 4, v246
	v_and_b32_e32 v248, 3, v214
	v_bfe_u32 v247, v214, 4, 2
	v_xor_b32_e32 v248, v248, v247
	v_lshlrev_b32_e32 v248, 4, v248
	v_add_u32_e32 v248, 0x80, v248
	v_mov_b32_e32 v249, 0
	v_lshl_or_b32 v246, s61, 6, v246
	v_mov_b64_e32 v[34:35], s[22:23]
	v_mad_u64_u32 v[34:35], s[42:43], v246, s73, v[34:35]
	v_lshl_add_u64 v[34:35], v[34:35], 0, v[248:249]
	v_lshl_add_u64 v[34:35], v[34:35], 0, s[92:93]
	s_mov_b64 s[42:43], 0

; __device__ __forceinline__ int crow(int r, int hi) { return (r & 3) + 8 * (r >> 2) + 4 * hi; }
; #define ATT_LAS __attribute__((address_space(3)))
; template <int DQK, int MODE> __device__ __forceinline__ void unit(const Desc& d, int q0, ATT_LAS char* shm, const float* biasg, float sinkl2) {
;     ...
;             { const ATT_LAS char* kb = shm + LDS_K + buf * KSLOT + hi * 1024 + r32 * 16;
; #pragma unroll
;               for (int d0 = 0; d0 < ND0; ++d0) {
;                   const bf16x8 b0 = *(const ATT_LAS bf16x8*)(kb + d0 * 2048);
;                   const bf16x8 b1 = *(const ATT_LAS bf16x8*)(kb + d0 * 2048 + 512);
;                   if (d0 == 0) { p0 = __builtin_amdgcn_mfma_f32_32x32x16_bf16(b0, qr[0], negm, 0, 0, 0); p1 = __builtin_amdgcn_mfma_f32_32x32x16_bf16(b1, qr[0], negm, 0, 0, 0); }
;                   else { p0 = __builtin_amdgcn_mfma_f32_32x32x16_bf16(b0, qr[d0], p0, 0, 0, 0); p1 = __builtin_amdgcn_mfma_f32_32x32x16_bf16(b1, qr[d0], p1, 0, 0, 0); } } }
;     ...
;                 const float f = __builtin_amdgcn_exp2f(-dl); l_reg *= f; if (hi == 0) wsf[r32] = f;
;                 asm volatile("s_waitcnt lgkmcnt(0)" ::: "memory");
; #pragma unroll
;                 for (int d_ = 0; d_ < 2; ++d_)
; #pragma unroll
;                     for (int r = 0; r < 16; ++r) o[d_][r] *= wsf[crow(r, hi)];
;                 if (MSUM) {
; #pragma unroll
;                     for (int r = 0; r < 16; ++r) lacc[r] *= wsf[crow(r, hi)];
.LBB0_586:
	s_mul_i32 s39, s60, 0x3000
	v_add_u32_e32 v238, s39, v209
	v_add_u32_e32 v239, s39, v208
	v_add_u32_e32 v234, s39, v221
	v_add_u32_e32 v235, s39, v223
	v_add_u32_e32 v236, s39, v252
	v_add_u32_e32 v237, s39, v253
	ds_read_b128 v[130:133], v234
	ds_read_b128 v[134:137], v234 offset:4096
	ds_read_b128 v[138:141], v235
	ds_read_b128 v[142:145], v235 offset:4096
	ds_read_b128 v[146:149], v236
	ds_read_b128 v[150:153], v236 offset:4096
	ds_read_b128 v[154:157], v237
	ds_read_b128 v[158:161], v237 offset:4096
	ds_read_b128 v[162:165], v238
	ds_read_b128 v[166:169], v238 offset:2048
	ds_read_b128 v[170:173], v239
	ds_read_b128 v[174:177], v239 offset:2048
	v_mov_b32_e32 v224, s40
	v_mov_b32_e32 v225, s40
	v_mov_b32_e32 v226, s40
	v_mov_b32_e32 v227, s40
	v_lshl_add_u32 v0, s60, 13, v219
	s_waitcnt lgkmcnt(11)
	v_mfma_f32_32x32x16_bf16 v[114:129], v[130:133], v[178:181], v[66:81]
	ds_read_b64_tr_b16 v[34:35], v0
	s_waitcnt lgkmcnt(11)
	v_mfma_f32_32x32x16_bf16 v[98:113], v[134:137], v[178:181], v[66:81]
	ds_read_b64_tr_b16 v[36:37], v0 offset:512
	s_waitcnt lgkmcnt(11)
	v_mfma_f32_32x32x16_bf16 v[114:129], v[138:141], v[182:185], v[114:129]
	ds_read_b64_tr_b16 v[38:39], v0 offset:1024
	s_waitcnt lgkmcnt(11)
	v_mfma_f32_32x32x16_bf16 v[98:113], v[142:145], v[182:185], v[98:113]
	ds_read_b64_tr_b16 v[40:41], v0 offset:1536
	s_waitcnt lgkmcnt(11)
	v_mfma_f32_32x32x16_bf16 v[114:129], v[146:149], v[186:189], v[114:129]
	ds_read_b64_tr_b16 v[42:43], v0 offset:2048
	s_waitcnt lgkmcnt(11)
	v_mfma_f32_32x32x16_bf16 v[98:113], v[150:153], v[186:189], v[98:113]
	ds_read_b64_tr_b16 v[44:45], v0 offset:2560
	s_waitcnt lgkmcnt(11)
	v_mfma_f32_32x32x16_bf16 v[114:129], v[154:157], v[190:193], v[114:129]
	ds_read_b64_tr_b16 v[46:47], v0 offset:3072
	s_waitcnt lgkmcnt(11)
	v_mfma_f32_32x32x16_bf16 v[98:113], v[158:161], v[190:193], v[98:113]
	ds_read_b64_tr_b16 v[48:49], v0 offset:3584
	s_waitcnt lgkmcnt(11)
	v_mfma_f32_32x32x16_bf16 v[114:129], v[162:165], v[194:197], v[114:129]
	ds_read_b64_tr_b16 v[50:51], v0 offset:4096
	s_waitcnt lgkmcnt(11)
	v_mfma_f32_32x32x16_bf16 v[98:113], v[166:169], v[194:197], v[98:113]
	ds_read_b64_tr_b16 v[52:53], v0 offset:4608
	s_waitcnt lgkmcnt(11)
	v_mfma_f32_32x32x16_bf16 v[114:129], v[170:173], v[198:201], v[114:129]
	ds_read_b64_tr_b16 v[54:55], v0 offset:5120
	s_waitcnt lgkmcnt(11)
	v_mfma_f32_32x32x16_bf16 v[98:113], v[174:177], v[198:201], v[98:113]
	ds_read_b64_tr_b16 v[56:57], v0 offset:5632
	ds_read_b64_tr_b16 v[58:59], v0 offset:6144
	ds_read_b64_tr_b16 v[60:61], v0 offset:6656
	ds_read_b64_tr_b16 v[62:63], v0 offset:7168
	ds_read_b64_tr_b16 v[64:65], v0 offset:7680
	s_nop 15
	s_nop 7
	s_nop 0
	v_max3_f32 v0, v114, v115, v98
	v_max3_f32 v222, v116, v117, v99
	s_nop 0
	v_max3_f32 v0, v0, v100, v101
	v_max3_f32 v222, v222, v120, v121
	s_nop 0
	v_max3_f32 v0, v0, v118, v119
	v_max3_f32 v222, v222, v104, v105
	s_nop 0
	v_max3_f32 v0, v0, v102, v103
	v_max3_f32 v222, v222, v124, v125
	s_nop 0
	v_max3_f32 v0, v0, v122, v123
	v_max3_f32 v222, v222, v108, v109
	s_nop 0
	v_max3_f32 v0, v0, v106, v107
	v_max3_f32 v222, v222, v128, v129
	s_nop 0
	v_max3_f32 v0, v0, v126, v127
	v_max3_f32 v222, v222, v112, v113
	s_nop 0
	v_max3_f32 v0, v0, v110, v111
	s_nop 0
	v_max_f32_e32 v0, v0, v222
	s_nop 0
	v_mov_b32_e32 v222, v0
	s_nop 1
	v_permlane32_swap_b32_e32 v0, v222
	v_max_f32_e32 v0, v0, v222
	s_cmp_lg_u32 s96, 0
	s_cbranch_scc0 .LBB0_591
	v_cmp_lt_f32_e32 vcc, s70, v0
	s_cbranch_vccz .LBB0_571
	v_max_f32_e32 v250, v0, v0
	v_max_f32_e32 v250, 0, v250
	s_and_saveexec_b64 s[42:43], s[4:5]
	v_exp_f32_e64 v251, -v250
	s_nop 0
	ds_write_b32 v218, v251 offset:40960
	s_or_b64 exec, exec, s[42:43]
	s_waitcnt lgkmcnt(0)
	v_lshl_add_u32 v251, v217, 4, s54
	ds_read_b128 v[234:237], v251 offset:40960
	ds_read_b128 v[238:241], v251 offset:40992
	ds_read_b128 v[242:245], v251 offset:41024
	ds_read_b128 v[246:249], v251 offset:41056
	v_add_f32_e32 v220, v220, v250
	v_xor_b32_e32 v81, 0x80000000, v220
	v_sub_f32_e32 v114, v114, v250
	v_sub_f32_e32 v115, v115, v250
	v_sub_f32_e32 v116, v116, v250
	v_sub_f32_e32 v117, v117, v250
	v_sub_f32_e32 v118, v118, v250
	v_sub_f32_e32 v119, v119, v250
	v_sub_f32_e32 v120, v120, v250
	v_sub_f32_e32 v121, v121, v250
	v_sub_f32_e32 v122, v122, v250
	v_sub_f32_e32 v123, v123, v250
	v_sub_f32_e32 v124, v124, v250
	v_sub_f32_e32 v125, v125, v250
	v_sub_f32_e32 v126, v126, v250
	v_sub_f32_e32 v127, v127, v250
	v_sub_f32_e32 v128, v128, v250
	v_sub_f32_e32 v129, v129, v250
	v_sub_f32_e32 v98, v98, v250
	v_sub_f32_e32 v99, v99, v250
	v_sub_f32_e32 v100, v100, v250
	v_sub_f32_e32 v101, v101, v250
	v_sub_f32_e32 v102, v102, v250
	v_sub_f32_e32 v103, v103, v250
	v_sub_f32_e32 v104, v104, v250
	v_sub_f32_e32 v105, v105, v250
	v_sub_f32_e32 v106, v106, v250
	v_sub_f32_e32 v107, v107, v250
	v_sub_f32_e32 v108, v108, v250
	v_sub_f32_e32 v109, v109, v250
	v_sub_f32_e32 v110, v110, v250
	v_sub_f32_e32 v111, v111, v250
	v_sub_f32_e32 v112, v112, v250
	v_sub_f32_e32 v113, v113, v250
	s_waitcnt lgkmcnt(0)
	v_pk_mul_f32 v[2:3], v[2:3], v[234:235]
	v_pk_mul_f32 v[4:5], v[4:5], v[236:237]
	v_pk_mul_f32 v[6:7], v[6:7], v[238:239]
	v_pk_mul_f32 v[8:9], v[8:9], v[240:241]
	v_pk_mul_f32 v[10:11], v[10:11], v[242:243]
	v_pk_mul_f32 v[12:13], v[12:13], v[244:245]
	v_pk_mul_f32 v[14:15], v[14:15], v[246:247]
	v_pk_mul_f32 v[16:17], v[16:17], v[248:249]
	v_pk_mul_f32 v[18:19], v[18:19], v[234:235]
	v_pk_mul_f32 v[20:21], v[20:21], v[236:237]
	v_pk_mul_f32 v[22:23], v[22:23], v[238:239]
	v_pk_mul_f32 v[24:25], v[24:25], v[240:241]
	v_pk_mul_f32 v[26:27], v[26:27], v[242:243]
	v_pk_mul_f32 v[28:29], v[28:29], v[244:245]
	v_pk_mul_f32 v[30:31], v[30:31], v[246:247]
	v_pk_mul_f32 v[32:33], v[32:33], v[248:249]
	v_pk_mul_f32 v[82:83], v[82:83], v[234:235]
	v_pk_mul_f32 v[84:85], v[84:85], v[236:237]
	v_pk_mul_f32 v[86:87], v[86:87], v[238:239]
	v_pk_mul_f32 v[88:89], v[88:89], v[240:241]
	v_pk_mul_f32 v[90:91], v[90:91], v[242:243]
	v_pk_mul_f32 v[92:93], v[92:93], v[244:245]
	v_pk_mul_f32 v[94:95], v[94:95], v[246:247]
	v_pk_mul_f32 v[96:97], v[96:97], v[248:249]
	v_mov_b32_e32 v80, v81
	v_mov_b32_e32 v79, v81
	v_mov_b32_e32 v78, v81
	v_mov_b32_e32 v77, v81
	v_mov_b32_e32 v76, v81
	v_mov_b32_e32 v75, v81
	v_mov_b32_e32 v74, v81
	v_mov_b32_e32 v73, v81
	v_mov_b32_e32 v72, v81
	v_mov_b32_e32 v71, v81
	v_mov_b32_e32 v70, v81
	v_mov_b32_e32 v69, v81
	v_mov_b32_e32 v68, v81
	v_mov_b32_e32 v67, v81
	v_mov_b32_e32 v66, v81
	s_branch .LBB0_571
